# phase0 weight transposes: loads of the next 128x128 tile issued before the current tile's LDS read/pack/store half (software pipelining across tiles, second half on private registers)
# speedup vs baseline: 1.0100x; 1.0100x over previous
.LBB0_14:
	s_mov_b32 s86, 0

.LBB0_44:
	s_or_b64 exec, exec, s[14:15]
	s_cmp_eq_u32 s86, 0
	s_cbranch_scc0 .Lp0_finish
	s_waitcnt vmcnt(0)
	s_branch .Lp0_proc1b
.Lp0_proc1:
	s_waitcnt vmcnt(4)
.Lp0_proc1b:
	ds_write2_b32 v51, v6, v7 offset1:1
	ds_write2_b32 v51, v8, v9 offset0:2 offset1:3
	v_add_u32_e32 v6, 0x2040, v51
	ds_write2_b32 v6, v2, v3 offset1:1
	v_add_u32_e32 v2, 0x2048, v51
	ds_write2_b32 v2, v4, v5 offset1:1
	v_add_u32_e32 v2, 0x4080, v51
	ds_write2_b32 v2, v14, v15 offset1:1
	v_add_u32_e32 v2, 0x4088, v51
	ds_write2_b32 v2, v16, v17 offset1:1
	v_add_u32_e32 v2, 0x60c0, v51
	ds_write2_b32 v2, v10, v11 offset1:1
	v_add_u32_e32 v2, 0x60c8, v51
	ds_write2_b32 v2, v12, v13 offset1:1
	v_add_u32_e32 v2, 0x8100, v51
	ds_write2_b32 v2, v22, v23 offset1:1
	v_add_u32_e32 v2, 0x8108, v51
	ds_write2_b32 v2, v24, v25 offset1:1
	v_add_u32_e32 v2, 0xa140, v51
	ds_write2_b32 v2, v18, v19 offset1:1
	v_add_u32_e32 v2, 0xa148, v51
	ds_write2_b32 v2, v20, v21 offset1:1
	v_add_u32_e32 v2, 0xc180, v51
	ds_write2_b32 v2, v30, v31 offset1:1
	v_add_u32_e32 v2, 0xc188, v51
	ds_write2_b32 v2, v32, v33 offset1:1
	v_add_u32_e32 v2, 0xe1c0, v51
	ds_write2_b32 v2, v26, v27 offset1:1
	v_add_u32_e32 v2, 0xe1c8, v51
	ds_write2_b32 v2, v28, v29 offset1:1
	s_lshl_b32 s88, s12, 1
	s_mov_b32 s89, 0
	s_mov_b32 s90, s25
	s_mov_b32 s86, 1
	s_add_i32 s24, s24, s2
	s_cmpk_lt_i32 s24, 0x6e0
	s_cbranch_scc1 .Lp0_load
.Lp0_finish:
	v_mov_b32_e32 v135, 0
	v_add_u32_e32 v102, 8, v52
	s_waitcnt lgkmcnt(0)
	s_barrier
	ds_read2st64_b32 v[106:107], v52 offset1:1
	ds_read2_b32 v[108:109], v52 offset0:129 offset1:193
	ds_read2st64_b32 v[110:111], v102 offset0:4 offset1:5
	v_add_u32_e32 v102, 12, v52
	ds_read2st64_b32 v[112:113], v102 offset0:6 offset1:7
	v_add_u32_e32 v102, 16, v52
	ds_read2st64_b32 v[114:115], v102 offset0:8 offset1:9
	v_add_u32_e32 v102, 20, v52
	ds_read2st64_b32 v[116:117], v102 offset0:10 offset1:11
	v_add_u32_e32 v102, 24, v52
	ds_read2st64_b32 v[118:119], v102 offset0:12 offset1:13
	v_add_u32_e32 v102, 28, v52
	ds_read2st64_b32 v[120:121], v102 offset0:14 offset1:15
	s_waitcnt lgkmcnt(6)
	v_cvt_pk_bf16_f32 v102, v106, v108
	v_add_u32_e32 v106, 0x400, v53
	ds_read2_b32 v[128:129], v106 offset0:2 offset1:131
	v_add_u32_e32 v106, 0x800, v53
	ds_read2_b32 v[130:131], v106 offset0:4 offset1:133
	v_add_u32_e32 v106, 0xc00, v53
	ds_read2_b32 v[126:127], v53 offset1:129
	ds_read2_b32 v[132:133], v106 offset0:6 offset1:135
	v_or_b32_e32 v134, s90, v41
	v_lshl_add_u64 v[122:123], v[36:37], 0, s[88:89]
	v_lshlrev_b64 v[124:125], 12, v[134:135]
	s_waitcnt lgkmcnt(8)
	v_cvt_pk_bf16_f32 v103, v110, v112
	s_waitcnt lgkmcnt(6)
	v_cvt_pk_bf16_f32 v104, v114, v116
	s_waitcnt lgkmcnt(4)
	v_cvt_pk_bf16_f32 v105, v118, v120
	v_lshl_add_u64 v[124:125], v[122:123], 0, v[124:125]
	v_or_b32_e32 v134, s90, v42
	global_store_dwordx4 v[124:125], v[102:105], off
	v_lshlrev_b64 v[124:125], 12, v[134:135]
	v_lshl_add_u64 v[124:125], v[122:123], 0, v[124:125]
	s_waitcnt lgkmcnt(1)
	v_cvt_pk_bf16_f32 v102, v126, v127
	v_cvt_pk_bf16_f32 v103, v128, v129
	v_cvt_pk_bf16_f32 v104, v130, v131
	s_waitcnt lgkmcnt(0)
	v_cvt_pk_bf16_f32 v105, v132, v133
	v_add_u32_e32 v110, 0x400, v54
	v_add_u32_e32 v112, 0x800, v54
	v_add_u32_e32 v114, 0xc00, v54
	global_store_dwordx4 v[124:125], v[102:105], off
	v_or_b32_e32 v134, s90, v43
	s_nop 0
	v_cvt_pk_bf16_f32 v102, v107, v109
	v_cvt_pk_bf16_f32 v103, v111, v113
	v_cvt_pk_bf16_f32 v104, v115, v117
	ds_read2_b32 v[108:109], v54 offset1:129
	ds_read2_b32 v[110:111], v110 offset0:2 offset1:131
	ds_read2_b32 v[112:113], v112 offset0:4 offset1:133
	ds_read2_b32 v[114:115], v114 offset0:6 offset1:135
	v_lshlrev_b64 v[106:107], 12, v[134:135]
	v_cvt_pk_bf16_f32 v105, v119, v121
	v_lshl_add_u64 v[106:107], v[122:123], 0, v[106:107]
	v_add_u32_e32 v134, s90, v44
	global_store_dwordx4 v[106:107], v[102:105], off
	v_lshlrev_b64 v[106:107], 12, v[134:135]
	v_lshl_add_u64 v[106:107], v[122:123], 0, v[106:107]
	s_waitcnt lgkmcnt(3)
	v_cvt_pk_bf16_f32 v102, v108, v109
	s_waitcnt lgkmcnt(2)
	v_cvt_pk_bf16_f32 v103, v110, v111
	s_waitcnt lgkmcnt(1)
	v_cvt_pk_bf16_f32 v104, v112, v113
	s_waitcnt lgkmcnt(0)
	v_cvt_pk_bf16_f32 v105, v114, v115
	global_store_dwordx4 v[106:107], v[102:105], off
	s_barrier
	s_cmpk_lt_i32 s24, 0x6e0
	s_cbranch_scc1 .Lp0_proc1
	s_branch .LBB0_51
